# cross-XCD sharing of phaseA(l+1) passes as well (owner runs its first 5 passes unclaimed, 36 helpers)
# speedup vs baseline: 1.0345x; 1.0345x over previous
;     ...
;     for (int pass = 0; pass * NWAVE < NU; ++pass) {
;         const int unit = pass * NWAVE + wave;
;         const bool active = unit < NU;
;         const int ucl = active ? unit : NU - 1;
;         const u32x4* bp = Bw + (size_t)(ucl * NT) * 64 + lane;
; __global__ void __launch_bounds__(NTHR) mega(Params p) {
;     ...
;         for (int t = tb; t < NTILE; t += G) if (t < 4) { phaseC<3>(p, l, t, lds); if (l + 1 < DEPTH) phaseA<3>(p, l + 1, t, lds); }
.LBB0_820:
	v_readlane_b32 s0, v255, 52
	v_readlane_b32 s1, v255, 53
	s_and_b64 vcc, exec, s[0:1]
	s_cbranch_vccnz .LBB0_781
	s_ashr_i32 s95, s94, 31
	s_lshl_b32 s28, s31, 13
	s_add_i32 s6, s31, 0x200
	s_lshl_b64 s[2:3], s[94:95], 9
	v_readlane_b32 s0, v255, 32
	s_add_u32 s0, s0, s2
	v_readlane_b32 s1, v255, 34
	s_addc_u32 s1, s1, s3
	v_readlane_b32 s7, v255, 36
	s_add_u32 s68, s7, s2
	v_readlane_b32 s2, v255, 38
	s_addc_u32 s69, s2, s3
	s_lshl_b64 s[2:3], s[94:95], 11
	v_readlane_b32 s7, v255, 40
	s_add_u32 s70, s7, s2
	v_readlane_b32 s7, v255, 44
	s_addc_u32 s71, s7, s3
	v_readlane_b32 s7, v255, 51
	s_add_u32 s72, s7, s2
	v_readlane_b32 s2, v255, 46
	s_addc_u32 s73, s2, s3
	s_lshl_b64 s[2:3], s[66:67], 11
	v_readlane_b32 s7, v253, 16
	v_mov_b32_e32 v0, v176
	s_add_u32 s66, s7, s2
	v_readlane_b32 s2, v253, 17
	s_addc_u32 s67, s2, s3
	v_lshlrev_b32_e32 v5, 3, v0
	v_and_b32_e32 v2, 63, v0
	v_readlane_b32 s2, v255, 47
	v_and_b32_e32 v10, 0x78, v5
	v_lshlrev_b32_e32 v5, 4, v0
	v_lshlrev_b32_e32 v2, 4, v2
	v_mov_b32_e32 v3, v1
	v_readlane_b32 s3, v255, 48
	v_and_b32_e32 v224, 0xf0, v5
	v_lshrrev_b32_e32 v5, 1, v0
	v_and_b32_e32 v4, 31, v0
	v_lshl_add_u64 v[156:157], s[2:3], 0, v[2:3]
	v_and_b32_e32 v5, 16, v5
	s_movk_i32 s2, 0x110
	v_ashrrev_i32_e32 v11, 4, v0
	v_mad_u32_u24 v225, v4, s2, v5
	v_lshl_or_b32 v4, v11, 10, v10
	v_ashrrev_i32_e32 v5, 31, v4
	v_lshl_add_u64 v[158:159], v[4:5], 1, s[66:67]
	v_add_u32_e32 v5, 0x200, v0
	v_ashrrev_i32_e32 v5, 4, v5
	v_ashrrev_i32_e32 v223, 6, v0
	v_lshl_or_b32 v6, v5, 10, v10
	v_add_u32_e32 v0, 0x400, v0
	v_ashrrev_i32_e32 v7, 31, v6
	v_ashrrev_i32_e32 v0, 4, v0
	v_lshl_add_u64 v[160:161], v[6:7], 1, s[66:67]
	v_subrev_u32_e32 v7, s94, v0
	v_lshl_or_b32 v7, v7, 10, v10
	v_add_u32_e32 v8, 0xff0000, v7
	v_mul_lo_u32 v226, v11, s2
	v_mul_lo_u32 v227, v5, s2
	v_mul_lo_u32 v228, v0, s2
	v_readlane_b32 s2, v255, 23
	v_add_u32_e32 v0, s37, v0
	v_ashrrev_i32_e32 v9, 31, v8
	s_lshl_b32 s29, s31, 15
	v_readlane_b32 s3, v255, 24
	v_lshl_or_b32 v0, v0, 10, v10
	v_lshl_add_u64 v[162:163], v[8:9], 1, s[66:67]
	s_lshl_b32 s52, s6, 14
	s_add_i32 s53, s29, 0xffffa000
	s_lshl_b32 s62, s6, 12
	s_add_i32 s63, s28, 0xffffd000
	v_lshl_add_u64 v[164:165], s[2:3], 0, v[2:3]
	v_or_b32_e32 v229, 0x80, v4
	v_add_u32_e32 v230, 0xff0080, v0
	v_or_b32_e32 v231, 0x80, v6
	s_mov_b32 s2, 0
	v_mov_b32_e32 v232, v223
	s_mov_b32 s88, 0
	s_waitcnt vmcnt(0)
	s_barrier
	v_readlane_b32 s10, v252, 10
	v_readlane_b32 s11, v252, 11
	s_lshl_b32 s6, s90, 2
	s_add_u32 s6, s6, s31
	s_lshl_b32 s6, s6, 3
	s_add_u32 s10, s10, s6
	s_addc_u32 s11, s11, 0
	v_readfirstlane_b32 s6, v223
	s_nop 3
	s_cmp_lg_u32 s6, 0
	s_cbranch_scc1 .Lm3a_claim
	s_mov_b64 s[12:13], exec
	s_mov_b64 exec, 1
	buffer_wbl2 sc1
	s_waitcnt vmcnt(0)
	s_getreg_b32 s6, hwreg(HW_REG_XCC_ID, 0, 4)
	s_add_u32 s6, s6, 1
	v_mov_b32_e32 v2, s6
	global_atomic_or v1, v2, s[10:11] offset:388
	s_mov_b64 exec, s[12:13]
.Lm3a_claim:
	s_mov_b32 s88, 0
	s_branch .Lm3a_go
.LBB0_822:
	s_or_b64 exec, exec, s[8:9]
	s_add_i32 s88, s88, 1
	s_cmp_lt_u32 s88, 5
	s_cbranch_scc1 .Lm3a_go
	v_readlane_b32 s10, v252, 10
	v_readlane_b32 s11, v252, 11
	s_lshl_b32 s6, s90, 2
	s_add_u32 s6, s6, s31
	s_lshl_b32 s6, s6, 3
	s_add_u32 s10, s10, s6
	s_addc_u32 s11, s11, 0
.Lm3a_dyn:
	v_readfirstlane_b32 s6, v223
	v_mov_b32_e32 v2, 0x20408
	s_nop 3
	s_cmp_lg_u32 s6, 0
	s_cbranch_scc1 .Lm3a_c_w
	s_mov_b64 s[12:13], exec
	s_mov_b64 exec, 1
	v_mov_b32_e32 v3, 1
	global_atomic_add v3, v1, v3, s[10:11] offset:128 sc0
	s_waitcnt vmcnt(0)
	ds_write_b32 v2, v3
	s_waitcnt lgkmcnt(0)
	s_mov_b64 exec, s[12:13]
.Lm3a_c_w:
	s_barrier
	ds_read_b32 v3, v2
	s_waitcnt lgkmcnt(0)
	v_readfirstlane_b32 s88, v3
	s_nop 3
	s_add_u32 s88, s88, 5
	s_cmp_ge_u32 s88, 9
	s_cbranch_scc1 .LBB0_781
.Lm3a_go:
	s_lshl_b32 s2, s88, 3
	v_add_u32_e32 v232, s2, v223

; template <int MT> DI void phaseA(const Params& p, int l, int t, unsigned char* lds) {
;     const int row0 = t * 64, d2 = MT == 3 ? tile_d2(t) : 0;
; __global__ void __launch_bounds__(NTHR) mega(Params p) {
;     ...
;         for (int t = tb; t < NTILE; t += G) if (t < 4) { phaseC<3>(p, l, t, lds); if (l + 1 < DEPTH) phaseA<3>(p, l + 1, t, lds); }
;         for (int t = tb; t < NTILE; t += G) if (t >= 4) { phaseC<2>(p, l, t, lds); if (l + 1 < DEPTH) phaseA<2>(p, l + 1, t, lds); }
.LBB0_921:
	v_readlane_b32 s0, v254, 57
	s_nop 3
	s_cmp_lt_u32 s0, 4
	s_cbranch_scc1 .Lha_done
	s_and_b32 s0, s0, 31
	s_cmp_gt_u32 s0, 4
	s_cbranch_scc1 .Lha_done
	v_writelane_b32 v246, s0, 0
	v_writelane_b32 v246, s1, 1
	v_writelane_b32 v246, s2, 2
	v_writelane_b32 v246, s3, 3
	v_writelane_b32 v246, s4, 4
	v_writelane_b32 v246, s5, 5
	v_writelane_b32 v246, s6, 6
	v_writelane_b32 v246, s7, 7
	v_writelane_b32 v246, s8, 8
	v_writelane_b32 v246, s9, 9
	v_writelane_b32 v246, s10, 10
	v_writelane_b32 v246, s11, 11
	v_writelane_b32 v246, s12, 12
	v_writelane_b32 v246, s13, 13
	v_writelane_b32 v246, s14, 14
	v_writelane_b32 v246, s15, 15
	v_writelane_b32 v246, s16, 16
	v_writelane_b32 v246, s17, 17
	v_writelane_b32 v246, s18, 18
	v_writelane_b32 v246, s19, 19
	v_writelane_b32 v246, s20, 20
	v_writelane_b32 v246, s21, 21
	v_writelane_b32 v246, s22, 22
	v_writelane_b32 v246, s23, 23
	v_writelane_b32 v246, s24, 24
	v_writelane_b32 v246, s25, 25
	v_writelane_b32 v246, s26, 26
	v_writelane_b32 v246, s27, 27
	v_writelane_b32 v246, s28, 28
	v_writelane_b32 v246, s29, 29
	v_writelane_b32 v246, s30, 30
	v_writelane_b32 v246, s31, 31
	v_writelane_b32 v246, s32, 32
	v_writelane_b32 v246, s33, 33
	v_writelane_b32 v246, s34, 34
	v_writelane_b32 v246, s35, 35
	v_writelane_b32 v246, s36, 36
	v_writelane_b32 v246, s37, 37
	v_writelane_b32 v246, s38, 38
	v_writelane_b32 v246, s39, 39
	v_writelane_b32 v246, s40, 40
	v_writelane_b32 v246, s41, 41
	v_writelane_b32 v246, s42, 42
	v_writelane_b32 v246, s43, 43
	v_writelane_b32 v246, s44, 44
	v_writelane_b32 v246, s45, 45
	v_writelane_b32 v246, s46, 46
	v_writelane_b32 v246, s47, 47
	v_writelane_b32 v246, s48, 48
	v_writelane_b32 v246, s49, 49
	v_writelane_b32 v246, s50, 50
	v_writelane_b32 v246, s51, 51
	v_writelane_b32 v246, s52, 52
	v_writelane_b32 v246, s53, 53
	v_writelane_b32 v246, s54, 54
	v_writelane_b32 v246, s55, 55
	v_writelane_b32 v246, s56, 56
	v_writelane_b32 v246, s57, 57
	v_writelane_b32 v246, s58, 58
	v_writelane_b32 v246, s59, 59
	v_writelane_b32 v246, s60, 60
	v_writelane_b32 v246, s61, 61
	v_writelane_b32 v246, s62, 62
	v_writelane_b32 v246, s63, 63
	v_writelane_b32 v247, s64, 0
	v_writelane_b32 v247, s65, 1
	v_writelane_b32 v247, s66, 2
	v_writelane_b32 v247, s67, 3
	v_writelane_b32 v247, s68, 4
	v_writelane_b32 v247, s69, 5
	v_writelane_b32 v247, s70, 6
	v_writelane_b32 v247, s71, 7
	v_writelane_b32 v247, s72, 8
	v_writelane_b32 v247, s73, 9
	v_writelane_b32 v247, s74, 10
	v_writelane_b32 v247, s75, 11
	v_writelane_b32 v247, s76, 12
	v_writelane_b32 v247, s77, 13
	v_writelane_b32 v247, s78, 14
	v_writelane_b32 v247, s79, 15
	v_writelane_b32 v247, s80, 16
	v_writelane_b32 v247, s81, 17
	v_writelane_b32 v247, s82, 18
	v_writelane_b32 v247, s83, 19
	v_writelane_b32 v247, s84, 20
	v_writelane_b32 v247, s85, 21
	v_writelane_b32 v247, s86, 22
	v_writelane_b32 v247, s87, 23
	v_writelane_b32 v247, s88, 24
	v_writelane_b32 v247, s89, 25
	v_writelane_b32 v247, s90, 26
	v_writelane_b32 v247, s91, 27
	v_writelane_b32 v247, s92, 28
	v_writelane_b32 v247, s93, 29
	v_writelane_b32 v247, s94, 30
	v_writelane_b32 v247, s95, 31
	v_writelane_b32 v247, s96, 32
	v_writelane_b32 v247, s97, 33
	v_writelane_b32 v247, s98, 34
	v_writelane_b32 v247, s99, 35
	v_writelane_b32 v247, s100, 36
	v_writelane_b32 v247, s101, 37
	v_writelane_b32 v247, vcc_lo, 38
	v_writelane_b32 v247, vcc_hi, 39
	s_getreg_b32 s14, hwreg(HW_REG_XCC_ID, 0, 4)
	v_readlane_b32 s16, v252, 10
	v_readlane_b32 s17, v252, 11
	v_readlane_b32 s18, v254, 57
	s_mov_b32 s19, 0
	s_mov_b32 s15, 0
	v_lshrrev_b32_e32 v223, 6, v176
.Lha_target:
	s_add_u32 s20, s18, s19
	s_and_b32 s20, s20, 3
	s_lshl_b32 s21, s90, 2
	s_add_u32 s21, s21, s20
	s_lshl_b32 s21, s21, 3
	s_add_u32 s22, s16, s21
	s_addc_u32 s23, s17, 0
	v_readfirstlane_b32 s24, v223
	v_mov_b32_e32 v3, 0x2040c
	s_nop 3
	s_cmp_lg_u32 s24, 0
	s_cbranch_scc1 .Lha_polled
	s_mov_b64 s[26:27], exec
	s_mov_b64 exec, 1
	s_mov_b32 s25, 0
; DI const bf16_t* wp(const Params& p, int l, size_t off) { return (const bf16_t*)(p.ws + OFF_WP) + (size_t)l * PW_LAYER + off; }
;     ...
; #pragma unroll 1
;     for (int pass = 0; pass * NWAVE < NU; ++pass) {
;         const int unit = pass * NWAVE + wave;
;         const bool active = unit < NU;
;         const int ucl = active ? unit : NU - 1;
;         const u32x4* bp = Bw + (size_t)(ucl * NT) * 64 + lane;
;         const size_t kstr = (size_t)NU * NT * 64;
; template <int MT> DI void phaseA(const Params& p, int l, int t, unsigned char* lds) {
;     const int row0 = t * 64, d2 = MT == 3 ? tile_d2(t) : 0;
;     unsigned char* ws = p.ws;
;     EpiMixIn<MT> e;
;     e.priv = (bf16_t*)(ws + OFF_PRIV) + (size_t)row0 * PRIVW;
;     e.ka = (bf16_t*)(ws + OFF_KA); e.kb = (bf16_t*)(ws + OFF_KB); e.vta = (bf16_t*)(ws + OFF_VTA); e.vtb = (bf16_t*)(ws + OFF_VTB);
;     e.tb0 = 2 * t; e.tb2 = SEQ / 32 + t;
;     e.d2 = d2;
;     e.oak = e.oav = e.obk = e.obv = nullptr;
;     e.sak = e.sav = e.sbk = e.sbv = nullptr;
;     if (row0 >= SEQ - 128) { const int pr = row0 - (SEQ - 128); e.oak = p.out + O_PAK + (size_t)l * 128 * 128 + (size_t)pr * 128; e.oav = p.out + O_PAV + (size_t)l * 128 * 128 + (size_t)pr * 128; }
;     if (row0 >= SEQ - 512) { const int pr = row0 - (SEQ - 512); e.obk = p.out + O_PBK + (size_t)l * 512 * 512 + (size_t)pr * 512; e.obv = p.out + O_PBV + (size_t)l * 512 * 512 + (size_t)pr * 512; }
;     if (MT == 3) {
;         const int sr = 32 * t;
;         e.sak = p.out + O_SAK + (size_t)l * 128 * 128 + (size_t)sr * 128; e.sav = p.out + O_SAV + (size_t)l * 128 * 128 + (size_t)sr * 128;
;         e.sbk = p.out + O_SBK + (size_t)l * 128 * 512 + (size_t)sr * 512; e.sbv = p.out + O_SBV + (size_t)l * 128 * 512 + (size_t)sr * 512;
;     }
;     gemm64<1024, MT>((const bf16_t*)(ws + OFF_XB) + (size_t)row0 * DM, DM, d2, wp(p, l, PW_IN), DIN / UW, lds, e);
.Lha_poll:
	global_load_dword v2, v1, s[22:23] offset:388 sc1
	s_waitcnt vmcnt(0)
	v_readfirstlane_b32 s21, v2
	s_nop 3
	s_cmp_lg_u32 s21, 0
	s_cbranch_scc1 .Lha_got
	s_sleep 40
	s_add_u32 s25, s25, 1
	s_cmp_lt_u32 s25, 500
	s_cbranch_scc1 .Lha_poll
.Lha_got:
	ds_write_b32 v3, v2
	s_waitcnt lgkmcnt(0)
	s_mov_b64 exec, s[26:27]
.Lha_polled:
	s_barrier
	ds_read_b32 v2, v3
	s_waitcnt lgkmcnt(0)
	v_readfirstlane_b32 s21, v2
	s_nop 3
	s_cmp_eq_u32 s21, 0
	s_cbranch_scc1 .Lha_next
	buffer_inv sc1
	s_waitcnt vmcnt(0)
	v_readlane_b32 s6, v252, 4
	v_readlane_b32 s7, v252, 5
	v_readlane_b32 s8, v252, 2
	v_readlane_b32 s9, v252, 3
	s_nop 3
	s_lshl_b32 s21, s20, 17
	s_add_u32 s66, s6, 0x7c00000
	s_addc_u32 s67, s7, 0
	s_add_u32 s66, s66, s21
	s_addc_u32 s67, s67, 0
	s_mul_i32 s21, s20, 0xb0000
	s_add_u32 s58, s6, 0x9c40000
	s_addc_u32 s59, s7, 0
	s_add_u32 s58, s58, s21
	s_addc_u32 s59, s59, 0
	s_lshl_b32 s21, s90, 16
	s_lshl_b32 s10, s20, 14
	s_add_u32 s21, s21, s10
	s_add_u32 s0, s8, 0x4d2c000
	s_addc_u32 s1, s9, 0
	s_add_u32 s0, s0, s21
	s_addc_u32 s1, s1, 0
	s_add_u32 s68, s8, 0x4d6c000
	s_addc_u32 s69, s9, 0
	s_add_u32 s68, s68, s21
	s_addc_u32 s69, s69, 0
	s_lshl_b32 s21, s90, 18
	s_lshl_b32 s10, s20, 16
	s_add_u32 s21, s21, s10
	s_add_u32 s70, s8, 0x4dac000
	s_addc_u32 s71, s9, 0
	s_add_u32 s70, s70, s21
	s_addc_u32 s71, s71, 0
	s_add_u32 s72, s8, 0x4eac000
	s_addc_u32 s73, s9, 0
	s_add_u32 s72, s72, s21
	s_addc_u32 s73, s73, 0
	s_lshl_b32 s94, s20, 5
	s_sub_u32 s37, 0, s94
	s_lshl_b32 s28, s20, 13
	s_lshl_b32 s29, s20, 15
	s_add_u32 s10, s20, 0x200
	s_lshl_b32 s52, s10, 14
	s_add_i32 s53, s29, 0xffffa000
	s_lshl_b32 s62, s10, 12
	s_add_i32 s63, s28, 0xffffd000
	s_movk_i32 s44, 0x1600
	s_movk_i32 s51, 0x4000
	s_mov_b32 s65, 0
	s_mov_b32 s81, 0x88000
	s_movk_i32 s83, 0x1000
	s_mul_i32 s21, s90, 0x1f00000
	s_add_u32 s12, s6, s21
	s_addc_u32 s13, s7, 0
	s_sub_u32 s10, s12, 0x1f00000
	s_subb_u32 s11, s13, 0
	v_mov_b32_e32 v0, v176
	v_lshlrev_b32_e32 v5, 3, v0
	v_and_b32_e32 v2, 63, v0
	s_mov_b32 s2, s12
	v_and_b32_e32 v10, 0x78, v5
	v_lshlrev_b32_e32 v5, 4, v0
	v_lshlrev_b32_e32 v2, 4, v2
	v_mov_b32_e32 v3, v1
	s_mov_b32 s3, s13
	v_and_b32_e32 v224, 0xf0, v5
	v_lshrrev_b32_e32 v5, 1, v0
	v_and_b32_e32 v4, 31, v0
	v_lshl_add_u64 v[156:157], s[2:3], 0, v[2:3]
	v_and_b32_e32 v5, 16, v5
	s_movk_i32 s2, 0x110
	v_ashrrev_i32_e32 v11, 4, v0
	v_mad_u32_u24 v225, v4, s2, v5
	v_lshl_or_b32 v4, v11, 10, v10
	v_ashrrev_i32_e32 v5, 31, v4
	v_lshl_add_u64 v[158:159], v[4:5], 1, s[66:67]
	v_add_u32_e32 v5, 0x200, v0
	v_ashrrev_i32_e32 v5, 4, v5
	v_ashrrev_i32_e32 v223, 6, v0
	v_lshl_or_b32 v6, v5, 10, v10
	v_add_u32_e32 v0, 0x400, v0
	v_ashrrev_i32_e32 v7, 31, v6
	v_ashrrev_i32_e32 v0, 4, v0
	v_lshl_add_u64 v[160:161], v[6:7], 1, s[66:67]
	v_subrev_u32_e32 v7, s94, v0
	v_lshl_or_b32 v7, v7, 10, v10
	v_add_u32_e32 v8, 0xff0000, v7
	v_mul_lo_u32 v226, v11, s2
	v_mul_lo_u32 v227, v5, s2
	v_mul_lo_u32 v228, v0, s2
	s_mov_b32 s2, s10
	v_add_u32_e32 v0, s37, v0
	v_ashrrev_i32_e32 v9, 31, v8
	s_mov_b32 s3, s11
	v_lshl_or_b32 v0, v0, 10, v10
	v_lshl_add_u64 v[162:163], v[8:9], 1, s[66:67]
	v_lshl_add_u64 v[164:165], s[2:3], 0, v[2:3]
	v_or_b32_e32 v229, 0x80, v4
	v_add_u32_e32 v230, 0xff0080, v0
	v_or_b32_e32 v231, 0x80, v6
	v_mov_b32_e32 v232, v223
.Lha_claim:
	v_readfirstlane_b32 s6, v223
	v_mov_b32_e32 v2, 0x20408
	s_nop 3
	s_cmp_lg_u32 s6, 0
	s_cbranch_scc1 .Lha_c_w
	s_mov_b64 s[26:27], exec
	s_mov_b64 exec, 1
	v_mov_b32_e32 v3, 1
	global_atomic_add v3, v1, v3, s[22:23] offset:128 sc0
	s_waitcnt vmcnt(0)
	ds_write_b32 v2, v3
	s_waitcnt lgkmcnt(0)
	s_mov_b64 exec, s[26:27]
.Lha_c_w:
	s_barrier
	ds_read_b32 v3, v2
	s_waitcnt lgkmcnt(0)
	v_readfirstlane_b32 s88, v3
	s_nop 3
	s_add_u32 s88, s88, 5
	s_cmp_ge_u32 s88, 9
	s_cbranch_scc1 .Lha_next
	s_lshl_b32 s2, s88, 3
	v_add_u32_e32 v232, s2, v223

;     ...
; #pragma unroll 1
;     for (int pass = 0; pass * NWAVE < NU; ++pass) {
;         const int unit = pass * NWAVE + wave;
; __global__ void __launch_bounds__(NTHR) mega(Params p) {
;     ...
;         for (int t = tb; t < NTILE; t += G) if (t < 4) { phaseC<3>(p, l, t, lds); if (l + 1 < DEPTH) phaseA<3>(p, l + 1, t, lds); }
;         for (int t = tb; t < NTILE; t += G) if (t >= 4) { phaseC<2>(p, l, t, lds); if (l + 1 < DEPTH) phaseA<2>(p, l + 1, t, lds); }
.Lha_latch:
	s_or_b64 exec, exec, s[8:9]
	s_branch .Lha_claim
.Lha_next:
	s_add_u32 s19, s19, 1
	s_cmp_lt_u32 s19, 4
	s_cbranch_scc1 .Lha_target
	v_readlane_b32 s0, v246, 0
	v_readlane_b32 s1, v246, 1
	v_readlane_b32 s2, v246, 2
	v_readlane_b32 s3, v246, 3
	v_readlane_b32 s4, v246, 4
	v_readlane_b32 s5, v246, 5
	v_readlane_b32 s6, v246, 6
	v_readlane_b32 s7, v246, 7
	v_readlane_b32 s8, v246, 8
	v_readlane_b32 s9, v246, 9
	v_readlane_b32 s10, v246, 10
	v_readlane_b32 s11, v246, 11
	v_readlane_b32 s12, v246, 12
	v_readlane_b32 s13, v246, 13
	v_readlane_b32 s14, v246, 14
	v_readlane_b32 s15, v246, 15
	v_readlane_b32 s16, v246, 16
	v_readlane_b32 s17, v246, 17
	v_readlane_b32 s18, v246, 18
	v_readlane_b32 s19, v246, 19
	v_readlane_b32 s20, v246, 20
	v_readlane_b32 s21, v246, 21
	v_readlane_b32 s22, v246, 22
	v_readlane_b32 s23, v246, 23
	v_readlane_b32 s24, v246, 24
	v_readlane_b32 s25, v246, 25
	v_readlane_b32 s26, v246, 26
	v_readlane_b32 s27, v246, 27
	v_readlane_b32 s28, v246, 28
	v_readlane_b32 s29, v246, 29
	v_readlane_b32 s30, v246, 30
	v_readlane_b32 s31, v246, 31
	v_readlane_b32 s32, v246, 32
	v_readlane_b32 s33, v246, 33
	v_readlane_b32 s34, v246, 34
	v_readlane_b32 s35, v246, 35
	v_readlane_b32 s36, v246, 36
	v_readlane_b32 s37, v246, 37
	v_readlane_b32 s38, v246, 38
	v_readlane_b32 s39, v246, 39
	v_readlane_b32 s40, v246, 40
	v_readlane_b32 s41, v246, 41
	v_readlane_b32 s42, v246, 42
	v_readlane_b32 s43, v246, 43
	v_readlane_b32 s44, v246, 44
	v_readlane_b32 s45, v246, 45
	v_readlane_b32 s46, v246, 46
	v_readlane_b32 s47, v246, 47
	v_readlane_b32 s48, v246, 48
	v_readlane_b32 s49, v246, 49
	v_readlane_b32 s50, v246, 50
	v_readlane_b32 s51, v246, 51
	v_readlane_b32 s52, v246, 52
	v_readlane_b32 s53, v246, 53
	v_readlane_b32 s54, v246, 54
	v_readlane_b32 s55, v246, 55
	v_readlane_b32 s56, v246, 56
	v_readlane_b32 s57, v246, 57
	v_readlane_b32 s58, v246, 58
	v_readlane_b32 s59, v246, 59
	v_readlane_b32 s60, v246, 60
	v_readlane_b32 s61, v246, 61
	v_readlane_b32 s62, v246, 62
	v_readlane_b32 s63, v246, 63
	v_readlane_b32 s64, v247, 0
	v_readlane_b32 s65, v247, 1
	v_readlane_b32 s66, v247, 2
	v_readlane_b32 s67, v247, 3
	v_readlane_b32 s68, v247, 4
	v_readlane_b32 s69, v247, 5
	v_readlane_b32 s70, v247, 6
	v_readlane_b32 s71, v247, 7
	v_readlane_b32 s72, v247, 8
	v_readlane_b32 s73, v247, 9
	v_readlane_b32 s74, v247, 10
	v_readlane_b32 s75, v247, 11
	v_readlane_b32 s76, v247, 12
	v_readlane_b32 s77, v247, 13
	v_readlane_b32 s78, v247, 14
	v_readlane_b32 s79, v247, 15
	v_readlane_b32 s80, v247, 16
	v_readlane_b32 s81, v247, 17
	v_readlane_b32 s82, v247, 18
	v_readlane_b32 s83, v247, 19
	v_readlane_b32 s84, v247, 20
	v_readlane_b32 s85, v247, 21
	v_readlane_b32 s86, v247, 22
	v_readlane_b32 s87, v247, 23
	v_readlane_b32 s88, v247, 24
	v_readlane_b32 s89, v247, 25
	v_readlane_b32 s90, v247, 26
	v_readlane_b32 s91, v247, 27
	v_readlane_b32 s92, v247, 28
	v_readlane_b32 s93, v247, 29
	v_readlane_b32 s94, v247, 30
	v_readlane_b32 s95, v247, 31
	v_readlane_b32 s96, v247, 32
	v_readlane_b32 s97, v247, 33
	v_readlane_b32 s98, v247, 34
	v_readlane_b32 s99, v247, 35
	v_readlane_b32 s100, v247, 36
	v_readlane_b32 s101, v247, 37
	v_readlane_b32 vcc_lo, v247, 38
	v_readlane_b32 vcc_hi, v247, 39
